# v57 plus NSA prologue early flag load and ring-wait move, loop counter ops after barrier, trip-0 redundant checks removed
# baseline (speedup 1.0000x reference)
.LBB0_254:
	ds_read_b128 v[130:133], v254
	ds_read_b128 v[134:137], v254 offset:1024
	ds_read_b128 v[138:141], v254 offset:2048
	ds_read_b128 v[142:145], v254 offset:3072
	s_add_u32 s94, s44, 0xfffc0080
	s_addc_u32 s95, s45, -1
	s_and_b64 s[46:47], s[46:47], exec
	s_cselect_b32 s95, s29, s95
	s_cselect_b32 s94, s43, s94
	s_cselect_b32 s47, s89, s92
	s_cselect_b32 s46, s90, s91
	s_mov_b32 m0, s79
	v_lshl_add_u64 v[162:163], s[44:45], 0, v[160:161]
	ds_read_b128 v[170:173], v165
	ds_read_b128 v[174:177], v165 offset:1024
	ds_read_b128 v[178:181], v165 offset:2048
	ds_read_b128 v[182:185], v165 offset:3072
	ds_read_b128 v[186:189], v165 offset:4096
	ds_read_b128 v[190:193], v165 offset:5120
	ds_read_b128 v[194:197], v165 offset:6144
	ds_read_b128 v[198:201], v165 offset:7168
	s_cmp_gt_u32 s85, 1
	s_cbranch_scc1 .Lpl_skip1

.Ldef_B_skip:
	s_add_u32 s46, s46, s18
	s_addc_u32 s47, s47, s19
	s_mov_b32 m0, s57
	v_lshl_add_u64 v[220:221], s[46:47], 0, v[148:149]
	global_load_lds_dwordx4 v148, s[46:47]
	s_add_u32 s46, s46, s30
	s_addc_u32 s47, s47, s31
	s_mov_b32 m0, s60
	v_lshl_add_u64 v[222:223], s[46:47], 0, v[148:149]
	global_load_lds_dwordx4 v148, s[46:47]
	s_cmp_gt_u32 s85, 1
	s_cbranch_scc0 .Lpl_w6
	s_waitcnt vmcnt(22)
	s_branch .Lpl_wdone

.Lgb_body2:
	ds_read_b128 v[130:133], v254
	ds_read_b128 v[134:137], v254 offset:1024
	ds_read_b128 v[138:141], v254 offset:2048
	ds_read_b128 v[142:145], v254 offset:3072
	s_mov_b32 m0, s79
	s_add_u32 s98, s44, s0
	s_addc_u32 s99, s45, s1
	ds_read_b128 v[170:173], v165
	ds_read_b128 v[174:177], v165 offset:1024
	ds_read_b128 v[178:181], v165 offset:2048
	ds_read_b128 v[182:185], v165 offset:3072
	ds_read_b128 v[186:189], v165 offset:4096
	ds_read_b128 v[190:193], v165 offset:5120
	ds_read_b128 v[194:197], v165 offset:6144
	ds_read_b128 v[198:201], v165 offset:7168
	global_load_lds_dwordx4 v160, s[44:45]
	s_mov_b32 m0, s80
	s_nop 0
	global_load_lds_dwordx4 v160, s[98:99]
	ds_read_b128 v[202:205], v254 offset:16384
	ds_read_b128 v[206:209], v254 offset:17408
	ds_read_b128 v[210:213], v254 offset:18432
	ds_read_b128 v[214:217], v254 offset:19456
	s_waitcnt lgkmcnt(0)
	s_barrier
	v_mfma_f32_16x16x32_f16 v[58:61], v[130:133], v[170:173], v[58:61]
	v_mfma_f32_16x16x32_f16 v[62:65], v[138:141], v[170:173], v[62:65]
	v_mfma_f32_16x16x32_f16 v[50:53], v[130:133], v[178:181], v[50:53]
	v_mfma_f32_16x16x32_f16 v[54:57], v[138:141], v[178:181], v[54:57]
	v_mfma_f32_16x16x32_f16 v[42:45], v[130:133], v[186:189], v[42:45]
	v_mfma_f32_16x16x32_f16 v[46:49], v[138:141], v[186:189], v[46:49]
	v_mfma_f32_16x16x32_f16 v[26:29], v[130:133], v[194:197], v[26:29]
	v_mfma_f32_16x16x32_f16 v[30:33], v[138:141], v[194:197], v[30:33]
	v_mfma_f32_16x16x32_f16 v[58:61], v[134:137], v[174:177], v[58:61]
	v_mfma_f32_16x16x32_f16 v[62:65], v[142:145], v[174:177], v[62:65]
	v_mfma_f32_16x16x32_f16 v[50:53], v[134:137], v[182:185], v[50:53]
	v_mfma_f32_16x16x32_f16 v[54:57], v[142:145], v[182:185], v[54:57]
	v_mfma_f32_16x16x32_f16 v[42:45], v[134:137], v[190:193], v[42:45]
	v_mfma_f32_16x16x32_f16 v[46:49], v[142:145], v[190:193], v[46:49]
	v_mfma_f32_16x16x32_f16 v[26:29], v[134:137], v[198:201], v[26:29]
	v_mfma_f32_16x16x32_f16 v[30:33], v[142:145], v[198:201], v[30:33]
	v_mfma_f32_16x16x32_f16 v[122:125], v[202:205], v[170:173], v[122:125]
	v_mfma_f32_16x16x32_f16 v[126:129], v[210:213], v[170:173], v[126:129]
	v_mfma_f32_16x16x32_f16 v[114:117], v[202:205], v[178:181], v[114:117]
	v_mfma_f32_16x16x32_f16 v[118:121], v[210:213], v[178:181], v[118:121]
	v_mfma_f32_16x16x32_f16 v[106:109], v[202:205], v[186:189], v[106:109]
	v_mfma_f32_16x16x32_f16 v[110:113], v[210:213], v[186:189], v[110:113]
	v_mfma_f32_16x16x32_f16 v[98:101], v[202:205], v[194:197], v[98:101]
	v_mfma_f32_16x16x32_f16 v[102:105], v[210:213], v[194:197], v[102:105]
	v_mfma_f32_16x16x32_f16 v[122:125], v[206:209], v[174:177], v[122:125]
	v_mfma_f32_16x16x32_f16 v[126:129], v[214:217], v[174:177], v[126:129]
	v_mfma_f32_16x16x32_f16 v[114:117], v[206:209], v[182:185], v[114:117]
	v_mfma_f32_16x16x32_f16 v[118:121], v[214:217], v[182:185], v[118:121]
	v_mfma_f32_16x16x32_f16 v[106:109], v[206:209], v[190:193], v[106:109]
	v_mfma_f32_16x16x32_f16 v[110:113], v[214:217], v[190:193], v[110:113]
	v_mfma_f32_16x16x32_f16 v[98:101], v[206:209], v[198:201], v[98:101]
	v_mfma_f32_16x16x32_f16 v[102:105], v[214:217], v[198:201], v[102:105]
	s_barrier
	s_mov_b32 m0, s51
	s_add_u32 s98, s94, s0
	s_addc_u32 s99, s95, s1
	ds_read_b128 v[170:173], v165 offset:16384
	ds_read_b128 v[174:177], v165 offset:17408
	ds_read_b128 v[178:181], v165 offset:18432
	ds_read_b128 v[182:185], v165 offset:19456
	ds_read_b128 v[186:189], v165 offset:20480
	ds_read_b128 v[190:193], v165 offset:21504
	ds_read_b128 v[194:197], v165 offset:22528
	ds_read_b128 v[198:201], v165 offset:23552
	global_load_lds_dwordx4 v146, s[94:95]
	s_mov_b32 m0, s56
	s_nop 0
	global_load_lds_dwordx4 v146, s[98:99]
	s_mov_b32 m0, s54
	s_add_u32 s96, s46, s30
	global_load_lds_dwordx4 v148, s[46:47]
	s_addc_u32 s97, s47, s31
	s_mov_b32 m0, s55
	global_load_lds_dwordx4 v148, s[96:97]
	s_add_u32 s44, s44, 0x100
	s_addc_u32 s45, s45, 0
	s_add_u32 s91, s91, 0x100
	s_addc_u32 s92, s92, 0
	s_add_u32 s46, s46, s18
	s_addc_u32 s47, s47, s19
	s_mov_b32 m0, s57
	global_load_lds_dwordx4 v148, s[46:47]
	s_add_u32 s46, s46, s30
	s_addc_u32 s47, s47, s31
	s_mov_b32 m0, s60
	global_load_lds_dwordx4 v148, s[46:47]
	s_waitcnt vmcnt(6)
	s_waitcnt lgkmcnt(0)
	s_barrier
	v_mfma_f32_16x16x32_f16 v[34:37], v[130:133], v[170:173], v[34:37]
	v_mfma_f32_16x16x32_f16 v[38:41], v[138:141], v[170:173], v[38:41]
	v_mfma_f32_16x16x32_f16 v[18:21], v[130:133], v[178:181], v[18:21]
	v_mfma_f32_16x16x32_f16 v[22:25], v[138:141], v[178:181], v[22:25]
	v_mfma_f32_16x16x32_f16 v[10:13], v[130:133], v[186:189], v[10:13]
	v_mfma_f32_16x16x32_f16 v[14:17], v[138:141], v[186:189], v[14:17]
	v_mfma_f32_16x16x32_f16 v[2:5], v[130:133], v[194:197], v[2:5]
	v_mfma_f32_16x16x32_f16 v[6:9], v[138:141], v[194:197], v[6:9]
	v_mfma_f32_16x16x32_f16 v[34:37], v[134:137], v[174:177], v[34:37]
	v_mfma_f32_16x16x32_f16 v[38:41], v[142:145], v[174:177], v[38:41]
	v_mfma_f32_16x16x32_f16 v[18:21], v[134:137], v[182:185], v[18:21]
	v_mfma_f32_16x16x32_f16 v[22:25], v[142:145], v[182:185], v[22:25]
	v_mfma_f32_16x16x32_f16 v[10:13], v[134:137], v[190:193], v[10:13]
	v_mfma_f32_16x16x32_f16 v[14:17], v[142:145], v[190:193], v[14:17]
	v_mfma_f32_16x16x32_f16 v[2:5], v[134:137], v[198:201], v[2:5]
	v_mfma_f32_16x16x32_f16 v[6:9], v[142:145], v[198:201], v[6:9]
	v_mfma_f32_16x16x32_f16 v[90:93], v[202:205], v[170:173], v[90:93]
	v_mfma_f32_16x16x32_f16 v[94:97], v[210:213], v[170:173], v[94:97]
	v_mfma_f32_16x16x32_f16 v[82:85], v[202:205], v[178:181], v[82:85]
	v_mfma_f32_16x16x32_f16 v[86:89], v[210:213], v[178:181], v[86:89]
	v_mfma_f32_16x16x32_f16 v[74:77], v[202:205], v[186:189], v[74:77]
	v_mfma_f32_16x16x32_f16 v[78:81], v[210:213], v[186:189], v[78:81]
	v_mfma_f32_16x16x32_f16 v[70:73], v[202:205], v[194:197], v[70:73]
	v_mfma_f32_16x16x32_f16 v[66:69], v[210:213], v[194:197], v[66:69]
	v_mfma_f32_16x16x32_f16 v[90:93], v[206:209], v[174:177], v[90:93]
	v_mfma_f32_16x16x32_f16 v[94:97], v[214:217], v[174:177], v[94:97]
	v_mfma_f32_16x16x32_f16 v[82:85], v[206:209], v[182:185], v[82:85]
	v_mfma_f32_16x16x32_f16 v[86:89], v[214:217], v[182:185], v[86:89]
	v_mfma_f32_16x16x32_f16 v[74:77], v[206:209], v[190:193], v[74:77]
	v_mfma_f32_16x16x32_f16 v[78:81], v[214:217], v[190:193], v[78:81]
	v_mfma_f32_16x16x32_f16 v[70:73], v[206:209], v[198:201], v[70:73]
	v_mfma_f32_16x16x32_f16 v[66:69], v[214:217], v[198:201], v[66:69]
	s_barrier
	ds_read_b128 v[130:133], v254 offset:32768
	ds_read_b128 v[134:137], v254 offset:33792
	ds_read_b128 v[138:141], v254 offset:34816
	ds_read_b128 v[142:145], v254 offset:35840
	s_mov_b32 m0, s61
	s_add_u32 s98, s94, s8
	s_addc_u32 s99, s95, s9
	ds_read_b128 v[170:173], v165 offset:32768
	ds_read_b128 v[174:177], v165 offset:33792
	ds_read_b128 v[178:181], v165 offset:34816
	ds_read_b128 v[182:185], v165 offset:35840
	ds_read_b128 v[186:189], v165 offset:36864
	ds_read_b128 v[190:193], v165 offset:37888
	ds_read_b128 v[194:197], v165 offset:38912
	ds_read_b128 v[198:201], v165 offset:39936
	global_load_lds_dwordx4 v146, s[98:99]
	s_add_u32 s98, s94, s12
	s_addc_u32 s99, s95, s13
	s_mov_b32 m0, s62
	s_nop 0
	global_load_lds_dwordx4 v146, s[98:99]
	ds_read_b128 v[202:205], v254 offset:49152
	ds_read_b128 v[206:209], v254 offset:50176
	ds_read_b128 v[210:213], v254 offset:51200
	ds_read_b128 v[214:217], v254 offset:52224
	s_waitcnt lgkmcnt(0)
	s_barrier
	v_mfma_f32_16x16x32_f16 v[58:61], v[130:133], v[170:173], v[58:61]
	v_mfma_f32_16x16x32_f16 v[62:65], v[138:141], v[170:173], v[62:65]
	v_mfma_f32_16x16x32_f16 v[50:53], v[130:133], v[178:181], v[50:53]
	v_mfma_f32_16x16x32_f16 v[54:57], v[138:141], v[178:181], v[54:57]
	v_mfma_f32_16x16x32_f16 v[42:45], v[130:133], v[186:189], v[42:45]
	v_mfma_f32_16x16x32_f16 v[46:49], v[138:141], v[186:189], v[46:49]
	v_mfma_f32_16x16x32_f16 v[26:29], v[130:133], v[194:197], v[26:29]
	v_mfma_f32_16x16x32_f16 v[30:33], v[138:141], v[194:197], v[30:33]
	v_mfma_f32_16x16x32_f16 v[58:61], v[134:137], v[174:177], v[58:61]
	v_mfma_f32_16x16x32_f16 v[62:65], v[142:145], v[174:177], v[62:65]
	v_mfma_f32_16x16x32_f16 v[50:53], v[134:137], v[182:185], v[50:53]
	v_mfma_f32_16x16x32_f16 v[54:57], v[142:145], v[182:185], v[54:57]
	v_mfma_f32_16x16x32_f16 v[42:45], v[134:137], v[190:193], v[42:45]
	v_mfma_f32_16x16x32_f16 v[46:49], v[142:145], v[190:193], v[46:49]
	v_mfma_f32_16x16x32_f16 v[26:29], v[134:137], v[198:201], v[26:29]
	v_mfma_f32_16x16x32_f16 v[30:33], v[142:145], v[198:201], v[30:33]
	v_mfma_f32_16x16x32_f16 v[122:125], v[202:205], v[170:173], v[122:125]
	v_mfma_f32_16x16x32_f16 v[126:129], v[210:213], v[170:173], v[126:129]
	v_mfma_f32_16x16x32_f16 v[114:117], v[202:205], v[178:181], v[114:117]
	v_mfma_f32_16x16x32_f16 v[118:121], v[210:213], v[178:181], v[118:121]
	v_mfma_f32_16x16x32_f16 v[106:109], v[202:205], v[186:189], v[106:109]
	v_mfma_f32_16x16x32_f16 v[110:113], v[210:213], v[186:189], v[110:113]
	v_mfma_f32_16x16x32_f16 v[98:101], v[202:205], v[194:197], v[98:101]
	v_mfma_f32_16x16x32_f16 v[102:105], v[210:213], v[194:197], v[102:105]
	v_mfma_f32_16x16x32_f16 v[122:125], v[206:209], v[174:177], v[122:125]
	v_mfma_f32_16x16x32_f16 v[126:129], v[214:217], v[174:177], v[126:129]
	v_mfma_f32_16x16x32_f16 v[114:117], v[206:209], v[182:185], v[114:117]
	v_mfma_f32_16x16x32_f16 v[118:121], v[214:217], v[182:185], v[118:121]
	v_mfma_f32_16x16x32_f16 v[106:109], v[206:209], v[190:193], v[106:109]
	v_mfma_f32_16x16x32_f16 v[110:113], v[214:217], v[190:193], v[110:113]
	v_mfma_f32_16x16x32_f16 v[98:101], v[206:209], v[198:201], v[98:101]
	v_mfma_f32_16x16x32_f16 v[102:105], v[214:217], v[198:201], v[102:105]
	s_barrier
	s_mov_b32 m0, s65
	s_add_u32 s98, s94, s14
	s_addc_u32 s99, s95, s15
	ds_read_b128 v[170:173], v165 offset:49152
	ds_read_b128 v[174:177], v165 offset:50176
	ds_read_b128 v[178:181], v165 offset:51200
	ds_read_b128 v[182:185], v165 offset:52224
	ds_read_b128 v[186:189], v165 offset:53248
	ds_read_b128 v[190:193], v165 offset:54272
	ds_read_b128 v[194:197], v165 offset:55296
	ds_read_b128 v[198:201], v165 offset:56320
	global_load_lds_dwordx4 v146, s[98:99]
	s_add_u32 s98, s94, s16
	s_addc_u32 s99, s95, s17
	s_mov_b32 m0, s72
	s_nop 0
	global_load_lds_dwordx4 v146, s[98:99]
	s_mov_b32 m0, s63
	s_add_u32 s96, s96, s14
	s_addc_u32 s97, s97, s15
	s_sub_u32 s98, s96, s30
	s_subb_u32 s99, s97, s31
	global_load_lds_dwordx4 v148, s[98:99]
	s_mov_b32 m0, s64
	s_nop 0
	global_load_lds_dwordx4 v148, s[96:97]
	s_mov_b32 m0, s73
	s_add_u32 s46, s46, s14
	s_addc_u32 s47, s47, s15
	s_sub_u32 s98, s46, s30
	s_subb_u32 s99, s47, s31
	global_load_lds_dwordx4 v148, s[98:99]
	s_mov_b32 m0, s74
	s_nop 0
	global_load_lds_dwordx4 v148, s[46:47]
	s_waitcnt vmcnt(6)
	s_waitcnt lgkmcnt(0)
	s_barrier
	v_mfma_f32_16x16x32_f16 v[34:37], v[130:133], v[170:173], v[34:37]
	v_mfma_f32_16x16x32_f16 v[38:41], v[138:141], v[170:173], v[38:41]
	v_mfma_f32_16x16x32_f16 v[18:21], v[130:133], v[178:181], v[18:21]
	v_mfma_f32_16x16x32_f16 v[22:25], v[138:141], v[178:181], v[22:25]
	v_mfma_f32_16x16x32_f16 v[10:13], v[130:133], v[186:189], v[10:13]
	v_mfma_f32_16x16x32_f16 v[14:17], v[138:141], v[186:189], v[14:17]
	v_mfma_f32_16x16x32_f16 v[2:5], v[130:133], v[194:197], v[2:5]
	v_mfma_f32_16x16x32_f16 v[6:9], v[138:141], v[194:197], v[6:9]
	v_mfma_f32_16x16x32_f16 v[34:37], v[134:137], v[174:177], v[34:37]
	v_mfma_f32_16x16x32_f16 v[38:41], v[142:145], v[174:177], v[38:41]
	v_mfma_f32_16x16x32_f16 v[18:21], v[134:137], v[182:185], v[18:21]
	v_mfma_f32_16x16x32_f16 v[22:25], v[142:145], v[182:185], v[22:25]
	v_mfma_f32_16x16x32_f16 v[10:13], v[134:137], v[190:193], v[10:13]
	v_mfma_f32_16x16x32_f16 v[14:17], v[142:145], v[190:193], v[14:17]
	v_mfma_f32_16x16x32_f16 v[2:5], v[134:137], v[198:201], v[2:5]
	v_mfma_f32_16x16x32_f16 v[6:9], v[142:145], v[198:201], v[6:9]
	v_mfma_f32_16x16x32_f16 v[90:93], v[202:205], v[170:173], v[90:93]
	v_mfma_f32_16x16x32_f16 v[94:97], v[210:213], v[170:173], v[94:97]
	v_mfma_f32_16x16x32_f16 v[82:85], v[202:205], v[178:181], v[82:85]
	v_mfma_f32_16x16x32_f16 v[86:89], v[210:213], v[178:181], v[86:89]
	v_mfma_f32_16x16x32_f16 v[74:77], v[202:205], v[186:189], v[74:77]
	v_mfma_f32_16x16x32_f16 v[78:81], v[210:213], v[186:189], v[78:81]
	v_mfma_f32_16x16x32_f16 v[70:73], v[202:205], v[194:197], v[70:73]
	v_mfma_f32_16x16x32_f16 v[66:69], v[210:213], v[194:197], v[66:69]
	v_mfma_f32_16x16x32_f16 v[90:93], v[206:209], v[174:177], v[90:93]
	v_mfma_f32_16x16x32_f16 v[94:97], v[214:217], v[174:177], v[94:97]
	v_mfma_f32_16x16x32_f16 v[82:85], v[206:209], v[182:185], v[82:85]
	v_mfma_f32_16x16x32_f16 v[86:89], v[214:217], v[182:185], v[86:89]
	v_mfma_f32_16x16x32_f16 v[74:77], v[206:209], v[190:193], v[74:77]
	v_mfma_f32_16x16x32_f16 v[78:81], v[214:217], v[190:193], v[78:81]
	v_mfma_f32_16x16x32_f16 v[70:73], v[206:209], v[198:201], v[70:73]
	v_mfma_f32_16x16x32_f16 v[66:69], v[214:217], v[198:201], v[66:69]
	s_barrier
	s_add_i32 s93, s93, 2
	s_cmp_gt_u32 s93, 13
	s_cbranch_scc1 .LBB0_264
	s_cmp_eq_u32 s93, 12
	s_cbranch_scc1 .Lgb_last
	s_add_u32 s94, s44, 0xfffc0080
	s_addc_u32 s95, s45, -1
	s_mov_b32 s47, s92
	s_mov_b32 s46, s91
	s_branch .Lgb_body2

.Lg2_body2:
	ds_read_b128 v[136:139], v254
	ds_read_b128 v[144:147], v254 offset:1024
	ds_read_b128 v[148:151], v254 offset:2048
	ds_read_b128 v[152:155], v254 offset:3072
	s_mov_b32 m0, s79
	ds_read_b128 v[156:159], v141
	ds_read_b128 v[160:163], v141 offset:1024
	ds_read_b128 v[164:167], v141 offset:2048
	ds_read_b128 v[168:171], v141 offset:3072
	ds_read_b128 v[172:175], v141 offset:4096
	ds_read_b128 v[176:179], v141 offset:5120
	ds_read_b128 v[180:183], v141 offset:6144
	ds_read_b128 v[184:187], v141 offset:7168
	global_load_lds_dwordx4 v134, s[44:45]
	s_mov_b32 m0, s80
	s_add_u32 s98, s44, s16
	s_addc_u32 s99, s45, s17
	global_load_lds_dwordx4 v134, s[98:99]
	ds_read_b128 v[188:191], v254 offset:16384
	ds_read_b128 v[192:195], v254 offset:17408
	ds_read_b128 v[196:199], v254 offset:18432
	ds_read_b128 v[200:203], v254 offset:19456
	s_waitcnt lgkmcnt(0)
	s_barrier
	v_mfma_f32_16x16x32_f16 v[118:121], v[136:139], v[156:159], v[118:121]
	v_mfma_f32_16x16x32_f16 v[114:117], v[148:151], v[156:159], v[114:117]
	v_mfma_f32_16x16x32_f16 v[102:105], v[136:139], v[164:167], v[102:105]
	v_mfma_f32_16x16x32_f16 v[98:101], v[148:151], v[164:167], v[98:101]
	v_mfma_f32_16x16x32_f16 v[86:89], v[136:139], v[172:175], v[86:89]
	v_mfma_f32_16x16x32_f16 v[82:85], v[148:151], v[172:175], v[82:85]
	v_mfma_f32_16x16x32_f16 v[66:69], v[136:139], v[180:183], v[66:69]
	v_mfma_f32_16x16x32_f16 v[54:57], v[148:151], v[180:183], v[54:57]
	v_mfma_f32_16x16x32_f16 v[118:121], v[144:147], v[160:163], v[118:121]
	v_mfma_f32_16x16x32_f16 v[114:117], v[152:155], v[160:163], v[114:117]
	v_mfma_f32_16x16x32_f16 v[102:105], v[144:147], v[168:171], v[102:105]
	v_mfma_f32_16x16x32_f16 v[98:101], v[152:155], v[168:171], v[98:101]
	v_mfma_f32_16x16x32_f16 v[86:89], v[144:147], v[176:179], v[86:89]
	v_mfma_f32_16x16x32_f16 v[82:85], v[152:155], v[176:179], v[82:85]
	v_mfma_f32_16x16x32_f16 v[66:69], v[144:147], v[184:187], v[66:69]
	v_mfma_f32_16x16x32_f16 v[54:57], v[152:155], v[184:187], v[54:57]
	v_mfma_f32_16x16x32_f16 v[122:125], v[188:191], v[156:159], v[122:125]
	v_mfma_f32_16x16x32_f16 v[126:129], v[196:199], v[156:159], v[126:129]
	v_mfma_f32_16x16x32_f16 v[106:109], v[188:191], v[164:167], v[106:109]
	v_mfma_f32_16x16x32_f16 v[110:113], v[196:199], v[164:167], v[110:113]
	v_mfma_f32_16x16x32_f16 v[90:93], v[188:191], v[172:175], v[90:93]
	v_mfma_f32_16x16x32_f16 v[94:97], v[196:199], v[172:175], v[94:97]
	v_mfma_f32_16x16x32_f16 v[74:77], v[188:191], v[180:183], v[74:77]
	v_mfma_f32_16x16x32_f16 v[78:81], v[196:199], v[180:183], v[78:81]
	v_mfma_f32_16x16x32_f16 v[122:125], v[192:195], v[160:163], v[122:125]
	v_mfma_f32_16x16x32_f16 v[126:129], v[200:203], v[160:163], v[126:129]
	v_mfma_f32_16x16x32_f16 v[106:109], v[192:195], v[168:171], v[106:109]
	v_mfma_f32_16x16x32_f16 v[110:113], v[200:203], v[168:171], v[110:113]
	v_mfma_f32_16x16x32_f16 v[90:93], v[192:195], v[176:179], v[90:93]
	v_mfma_f32_16x16x32_f16 v[94:97], v[200:203], v[176:179], v[94:97]
	v_mfma_f32_16x16x32_f16 v[74:77], v[192:195], v[184:187], v[74:77]
	v_mfma_f32_16x16x32_f16 v[78:81], v[200:203], v[184:187], v[78:81]
	s_barrier
	s_mov_b32 m0, s56
	ds_read_b128 v[156:159], v141 offset:16384
	ds_read_b128 v[160:163], v141 offset:17408
	ds_read_b128 v[164:167], v141 offset:18432
	ds_read_b128 v[168:171], v141 offset:19456
	ds_read_b128 v[172:175], v141 offset:20480
	ds_read_b128 v[176:179], v141 offset:21504
	ds_read_b128 v[180:183], v141 offset:22528
	ds_read_b128 v[184:187], v141 offset:23552
	global_load_lds_dwordx4 v130, s[46:47]
	s_mov_b32 m0, s59
	s_add_u32 s98, s46, s16
	s_addc_u32 s99, s47, s17
	global_load_lds_dwordx4 v130, s[98:99]
	s_mov_b32 m0, s57
	global_load_lds_dwordx4 v132, s[86:87]
	s_mov_b32 m0, s58
	s_add_u32 s98, s86, s14
	s_addc_u32 s99, s87, s15
	global_load_lds_dwordx4 v132, s[98:99]
	s_add_u32 s44, s44, 0x100
	s_addc_u32 s45, s45, 0
	s_add_u32 s51, s51, 0x100
	s_addc_u32 s84, s84, 0
	s_mov_b32 m0, s60
	s_add_u32 s98, s86, s18
	s_addc_u32 s99, s87, s19
	global_load_lds_dwordx4 v132, s[98:99]
	s_mov_b32 m0, s61
	s_add_u32 s98, s86, s16
	s_addc_u32 s99, s87, s17
	global_load_lds_dwordx4 v132, s[98:99]
	s_waitcnt vmcnt(6)
	s_waitcnt lgkmcnt(0)
	s_barrier
	v_mfma_f32_16x16x32_f16 v[58:61], v[136:139], v[156:159], v[58:61]
	v_mfma_f32_16x16x32_f16 v[50:53], v[148:151], v[156:159], v[50:53]
	v_mfma_f32_16x16x32_f16 v[38:41], v[136:139], v[164:167], v[38:41]
	v_mfma_f32_16x16x32_f16 v[34:37], v[148:151], v[164:167], v[34:37]
	v_mfma_f32_16x16x32_f16 v[22:25], v[136:139], v[172:175], v[22:25]
	v_mfma_f32_16x16x32_f16 v[18:21], v[148:151], v[172:175], v[18:21]
	v_mfma_f32_16x16x32_f16 v[10:13], v[136:139], v[180:183], v[10:13]
	v_mfma_f32_16x16x32_f16 v[6:9], v[148:151], v[180:183], v[6:9]
	v_mfma_f32_16x16x32_f16 v[58:61], v[144:147], v[160:163], v[58:61]
	v_mfma_f32_16x16x32_f16 v[50:53], v[152:155], v[160:163], v[50:53]
	v_mfma_f32_16x16x32_f16 v[38:41], v[144:147], v[168:171], v[38:41]
	v_mfma_f32_16x16x32_f16 v[34:37], v[152:155], v[168:171], v[34:37]
	v_mfma_f32_16x16x32_f16 v[22:25], v[144:147], v[176:179], v[22:25]
	v_mfma_f32_16x16x32_f16 v[18:21], v[152:155], v[176:179], v[18:21]
	v_mfma_f32_16x16x32_f16 v[10:13], v[144:147], v[184:187], v[10:13]
	v_mfma_f32_16x16x32_f16 v[6:9], v[152:155], v[184:187], v[6:9]
	v_mfma_f32_16x16x32_f16 v[62:65], v[188:191], v[156:159], v[62:65]
	v_mfma_f32_16x16x32_f16 v[70:73], v[196:199], v[156:159], v[70:73]
	v_mfma_f32_16x16x32_f16 v[42:45], v[188:191], v[164:167], v[42:45]
	v_mfma_f32_16x16x32_f16 v[46:49], v[196:199], v[164:167], v[46:49]
	v_mfma_f32_16x16x32_f16 v[26:29], v[188:191], v[172:175], v[26:29]
	v_mfma_f32_16x16x32_f16 v[30:33], v[196:199], v[172:175], v[30:33]
	v_mfma_f32_16x16x32_f16 v[14:17], v[188:191], v[180:183], v[14:17]
	v_mfma_f32_16x16x32_f16 v[2:5], v[196:199], v[180:183], v[2:5]
	v_mfma_f32_16x16x32_f16 v[62:65], v[192:195], v[160:163], v[62:65]
	v_mfma_f32_16x16x32_f16 v[70:73], v[200:203], v[160:163], v[70:73]
	v_mfma_f32_16x16x32_f16 v[42:45], v[192:195], v[168:171], v[42:45]
	v_mfma_f32_16x16x32_f16 v[46:49], v[200:203], v[168:171], v[46:49]
	v_mfma_f32_16x16x32_f16 v[26:29], v[192:195], v[176:179], v[26:29]
	v_mfma_f32_16x16x32_f16 v[30:33], v[200:203], v[176:179], v[30:33]
	v_mfma_f32_16x16x32_f16 v[14:17], v[192:195], v[184:187], v[14:17]
	v_mfma_f32_16x16x32_f16 v[2:5], v[200:203], v[184:187], v[2:5]
	s_barrier
	ds_read_b128 v[136:139], v254 offset:32768
	ds_read_b128 v[144:147], v254 offset:33792
	ds_read_b128 v[148:151], v254 offset:34816
	ds_read_b128 v[152:155], v254 offset:35840
	s_mov_b32 m0, s62
	ds_read_b128 v[156:159], v141 offset:32768
	ds_read_b128 v[160:163], v141 offset:33792
	ds_read_b128 v[164:167], v141 offset:34816
	ds_read_b128 v[168:171], v141 offset:35840
	ds_read_b128 v[172:175], v141 offset:36864
	ds_read_b128 v[176:179], v141 offset:37888
	ds_read_b128 v[180:183], v141 offset:38912
	ds_read_b128 v[184:187], v141 offset:39936
	s_add_u32 s98, s46, s20
	s_addc_u32 s99, s47, s21
	global_load_lds_dwordx4 v130, s[98:99]
	s_mov_b32 m0, s63
	s_add_u32 s98, s46, s22
	s_addc_u32 s99, s47, s23
	global_load_lds_dwordx4 v130, s[98:99]
	ds_read_b128 v[188:191], v254 offset:49152
	ds_read_b128 v[192:195], v254 offset:50176
	ds_read_b128 v[196:199], v254 offset:51200
	ds_read_b128 v[200:203], v254 offset:52224
	s_waitcnt lgkmcnt(0)
	s_barrier
	v_mfma_f32_16x16x32_f16 v[118:121], v[136:139], v[156:159], v[118:121]
	v_mfma_f32_16x16x32_f16 v[114:117], v[148:151], v[156:159], v[114:117]
	v_mfma_f32_16x16x32_f16 v[102:105], v[136:139], v[164:167], v[102:105]
	v_mfma_f32_16x16x32_f16 v[98:101], v[148:151], v[164:167], v[98:101]
	v_mfma_f32_16x16x32_f16 v[86:89], v[136:139], v[172:175], v[86:89]
	v_mfma_f32_16x16x32_f16 v[82:85], v[148:151], v[172:175], v[82:85]
	v_mfma_f32_16x16x32_f16 v[66:69], v[136:139], v[180:183], v[66:69]
	v_mfma_f32_16x16x32_f16 v[54:57], v[148:151], v[180:183], v[54:57]
	v_mfma_f32_16x16x32_f16 v[118:121], v[144:147], v[160:163], v[118:121]
	v_mfma_f32_16x16x32_f16 v[114:117], v[152:155], v[160:163], v[114:117]
	v_mfma_f32_16x16x32_f16 v[102:105], v[144:147], v[168:171], v[102:105]
	v_mfma_f32_16x16x32_f16 v[98:101], v[152:155], v[168:171], v[98:101]
	v_mfma_f32_16x16x32_f16 v[86:89], v[144:147], v[176:179], v[86:89]
	v_mfma_f32_16x16x32_f16 v[82:85], v[152:155], v[176:179], v[82:85]
	v_mfma_f32_16x16x32_f16 v[66:69], v[144:147], v[184:187], v[66:69]
	v_mfma_f32_16x16x32_f16 v[54:57], v[152:155], v[184:187], v[54:57]
	v_mfma_f32_16x16x32_f16 v[122:125], v[188:191], v[156:159], v[122:125]
	v_mfma_f32_16x16x32_f16 v[126:129], v[196:199], v[156:159], v[126:129]
	v_mfma_f32_16x16x32_f16 v[106:109], v[188:191], v[164:167], v[106:109]
	v_mfma_f32_16x16x32_f16 v[110:113], v[196:199], v[164:167], v[110:113]
	v_mfma_f32_16x16x32_f16 v[90:93], v[188:191], v[172:175], v[90:93]
	v_mfma_f32_16x16x32_f16 v[94:97], v[196:199], v[172:175], v[94:97]
	v_mfma_f32_16x16x32_f16 v[74:77], v[188:191], v[180:183], v[74:77]
	v_mfma_f32_16x16x32_f16 v[78:81], v[196:199], v[180:183], v[78:81]
	v_mfma_f32_16x16x32_f16 v[122:125], v[192:195], v[160:163], v[122:125]
	v_mfma_f32_16x16x32_f16 v[126:129], v[200:203], v[160:163], v[126:129]
	v_mfma_f32_16x16x32_f16 v[106:109], v[192:195], v[168:171], v[106:109]
	v_mfma_f32_16x16x32_f16 v[110:113], v[200:203], v[168:171], v[110:113]
	v_mfma_f32_16x16x32_f16 v[90:93], v[192:195], v[176:179], v[90:93]
	v_mfma_f32_16x16x32_f16 v[94:97], v[200:203], v[176:179], v[94:97]
	v_mfma_f32_16x16x32_f16 v[74:77], v[192:195], v[184:187], v[74:77]
	v_mfma_f32_16x16x32_f16 v[78:81], v[200:203], v[184:187], v[78:81]
	s_barrier
	s_mov_b32 m0, s72
	ds_read_b128 v[156:159], v141 offset:49152
	ds_read_b128 v[160:163], v141 offset:50176
	ds_read_b128 v[164:167], v141 offset:51200
	ds_read_b128 v[168:171], v141 offset:52224
	ds_read_b128 v[172:175], v141 offset:53248
	ds_read_b128 v[176:179], v141 offset:54272
	ds_read_b128 v[180:183], v141 offset:55296
	ds_read_b128 v[184:187], v141 offset:56320
	s_add_u32 s98, s46, s24
	s_addc_u32 s99, s47, s25
	global_load_lds_dwordx4 v130, s[98:99]
	s_mov_b32 m0, s73
	s_add_u32 s98, s46, s28
	s_addc_u32 s99, s47, s29
	global_load_lds_dwordx4 v130, s[98:99]
	s_mov_b32 m0, s64
	s_add_u32 s98, s86, s24
	s_addc_u32 s99, s87, s25
	global_load_lds_dwordx4 v132, s[98:99]
	s_mov_b32 m0, s65
	s_add_u32 s98, s86, s26
	s_addc_u32 s99, s87, s27
	global_load_lds_dwordx4 v132, s[98:99]
	s_mov_b32 m0, s74
	s_add_u32 s98, s86, s30
	s_addc_u32 s99, s87, s31
	global_load_lds_dwordx4 v132, s[98:99]
	s_mov_b32 m0, s75
	s_add_u32 s98, s86, s28
	s_addc_u32 s99, s87, s29
	global_load_lds_dwordx4 v132, s[98:99]
	s_waitcnt vmcnt(6)
	s_waitcnt lgkmcnt(0)
	s_barrier
	v_mfma_f32_16x16x32_f16 v[58:61], v[136:139], v[156:159], v[58:61]
	v_mfma_f32_16x16x32_f16 v[50:53], v[148:151], v[156:159], v[50:53]
	v_mfma_f32_16x16x32_f16 v[38:41], v[136:139], v[164:167], v[38:41]
	v_mfma_f32_16x16x32_f16 v[34:37], v[148:151], v[164:167], v[34:37]
	v_mfma_f32_16x16x32_f16 v[22:25], v[136:139], v[172:175], v[22:25]
	v_mfma_f32_16x16x32_f16 v[18:21], v[148:151], v[172:175], v[18:21]
	v_mfma_f32_16x16x32_f16 v[10:13], v[136:139], v[180:183], v[10:13]
	v_mfma_f32_16x16x32_f16 v[6:9], v[148:151], v[180:183], v[6:9]
	v_mfma_f32_16x16x32_f16 v[58:61], v[144:147], v[160:163], v[58:61]
	v_mfma_f32_16x16x32_f16 v[50:53], v[152:155], v[160:163], v[50:53]
	v_mfma_f32_16x16x32_f16 v[38:41], v[144:147], v[168:171], v[38:41]
	v_mfma_f32_16x16x32_f16 v[34:37], v[152:155], v[168:171], v[34:37]
	v_mfma_f32_16x16x32_f16 v[22:25], v[144:147], v[176:179], v[22:25]
	v_mfma_f32_16x16x32_f16 v[18:21], v[152:155], v[176:179], v[18:21]
	v_mfma_f32_16x16x32_f16 v[10:13], v[144:147], v[184:187], v[10:13]
	v_mfma_f32_16x16x32_f16 v[6:9], v[152:155], v[184:187], v[6:9]
	v_mfma_f32_16x16x32_f16 v[62:65], v[188:191], v[156:159], v[62:65]
	v_mfma_f32_16x16x32_f16 v[70:73], v[196:199], v[156:159], v[70:73]
	v_mfma_f32_16x16x32_f16 v[42:45], v[188:191], v[164:167], v[42:45]
	v_mfma_f32_16x16x32_f16 v[46:49], v[196:199], v[164:167], v[46:49]
	v_mfma_f32_16x16x32_f16 v[26:29], v[188:191], v[172:175], v[26:29]
	v_mfma_f32_16x16x32_f16 v[30:33], v[196:199], v[172:175], v[30:33]
	v_mfma_f32_16x16x32_f16 v[14:17], v[188:191], v[180:183], v[14:17]
	v_mfma_f32_16x16x32_f16 v[2:5], v[196:199], v[180:183], v[2:5]
	v_mfma_f32_16x16x32_f16 v[62:65], v[192:195], v[160:163], v[62:65]
	v_mfma_f32_16x16x32_f16 v[70:73], v[200:203], v[160:163], v[70:73]
	v_mfma_f32_16x16x32_f16 v[42:45], v[192:195], v[168:171], v[42:45]
	v_mfma_f32_16x16x32_f16 v[46:49], v[200:203], v[168:171], v[46:49]
	v_mfma_f32_16x16x32_f16 v[26:29], v[192:195], v[176:179], v[26:29]
	v_mfma_f32_16x16x32_f16 v[30:33], v[200:203], v[176:179], v[30:33]
	v_mfma_f32_16x16x32_f16 v[14:17], v[192:195], v[184:187], v[14:17]
	v_mfma_f32_16x16x32_f16 v[2:5], v[200:203], v[184:187], v[2:5]
	s_barrier
	s_add_i32 s85, s85, 2
	s_cmp_gt_u32 s85, 29
	s_cbranch_scc1 .LBB0_846
	s_cmp_eq_u32 s85, 28
	s_cbranch_scc1 .LBB0_844
	s_add_u32 s46, s44, 0xffe80080
	s_addc_u32 s47, s45, -1
	s_mov_b32 s87, s84
	s_mov_b32 s86, s51
	s_branch .Lg2_body2
